# MoBA: waves 0-3 skip the final band step, waves 0-5 skip the drain (exact zero contributions)
# speedup vs baseline: 1.0085x; 1.0035x over previous
;   #define RESC() do{ if(resc){ asm volatile("s_waitcnt lgkmcnt(0)":::"memory"); \
;       _Pragma("unroll") for(int d_=0;d_<2;++d_) _Pragma("unroll") for(int r=0;r<16;++r)o[d_][r]*=wsf[crow(r,hi)]; } }while(0)
;   #define ROT() do{sl_prev=sl_cur;sl_cur=sl_next;sl_next=(sl_next==(NSLOT-1)*SLOTB)?0:sl_next+SLOTB;}while(0)
;   #define ENDW(tt) do{ if((tt)+3<NT){WAIT_BAR(2);} else if((tt)+2<NT){WAIT_BAR(1);} else {WAIT_BAR(0);} }while(0)
; template<int THRL,int MODE,int DM,bool DRY=false> __device__ __forceinline__ void attn_unit(int b,int h,int qb,const bf16*Q,const bf16*__restrict__ K,const bf16*__restrict__ V,bf16*O,const bf16*__restrict__ Z,const float*__restrict__ XP,const int*__restrict__ TS,volatile unsigned*lw,unsigned nxt,cha ...
;     ...
;     STEP(pB0,pB1,pA0,pA1,t,(t+3<NT),(t+1<NT),(t+1<NT));       ENDW(t);   RESC(); ROT();
;     STEP(pA0,pA1,pB0,pB1,t+1,(t+4<NT),(t+2<NT),(t+2<NT));     ENDW(t+1); RESC(); ROT();
;   }
;   STEP(pB0,pB1,pA0,pA1,NT-1,false,false,false); RESC();
.LBB0_974:
	s_cmp_gt_u32 s65, 3
	s_cbranch_scc1 .Lmoba_fin_go
	v_mov_b32_e32 v112, v80
	v_lshl_add_u32 v98, v243, 2, s63
	s_branch .LBB0_977

; #define SBAR() __builtin_amdgcn_sched_barrier(0)
;   #define PKW(P,B) cvtpk_s(P[B],P[B+1])
; template<int THRL,int MODE,int DM,bool DRY=false> __device__ __forceinline__ void attn_unit(int b,int h,int qb,const bf16*Q,const bf16*__restrict__ K,const bf16*__restrict__ V,bf16*O,const bf16*__restrict__ Z,const float*__restrict__ XP,const int*__restrict__ TS,volatile unsigned*lw,unsigned nxt,cha ...
;     ...
;   const bf16*Zw=Z+(rowbase+q0+wid*QBLK)*DM+h*D; u32x4 zpre[4];
;   #pragma unroll
;   for(int i=0;i<4;++i)zpre[i]=*(const u32x4*)(Zw+(long)(i*8+(lane>>3))*DM+(lane&7)*8);
;   { float sacc=pB0[0]+pB0[1]; _Pragma("unroll") for(int r=2;r<16;++r)sacc+=pB0[r]; _Pragma("unroll") for(int r=0;r<16;++r)sacc+=pB1[r]; l_reg+=sacc;
;     pw0=(u32x4){PKW(pB0,0),PKW(pB0,2),PKW(pB0,4),PKW(pB0,6)};pw1=(u32x4){PKW(pB0,8),PKW(pB0,10),PKW(pB0,12),PKW(pB0,14)};pw2=(u32x4){PKW(pB1,0),PKW(pB1,2),PKW(pB1,4),PKW(pB1,6)};pw3=(u32x4){PKW(pB1,8),PKW(pB1,10),PKW(pB1,12),PKW(pB1,14)};
;     SBAR(); pv(o,vb0+sl_cur,PAF(0),PAF(1),PAF(2),PAF(3)); }
;     ...
;   if(lw!=nullptr&&tid==0)lw[0]=nxt;
.LBB0_977:
	s_cmp_lg_u32 0, -1
	s_cselect_b32 s8, 0, 0
	s_add_i32 s10, s8, 0x6000
	s_add_u32 s8, s87, s60
	s_addc_u32 s9, s88, s61
	s_add_u32 s8, s8, s62
	v_lshrrev_b32_e32 v99, 3, v239
	v_and_b32_e32 v80, 56, v242
	s_addc_u32 s9, s9, 0
	v_lshlrev_b32_e32 v222, 1, v80
	v_mul_u32_u24_e32 v82, 0x1a00, v99
	v_lshl_add_u64 v[80:81], s[8:9], 0, v[222:223]
	v_lshlrev_b32_e32 v96, 1, v82
	v_mov_b32_e32 v97, v223
	v_lshl_add_u64 v[80:81], v[80:81], 0, v[96:97]
	v_add_co_u32_e32 v82, vcc, s1, v80
	v_add3_u32 v97, v244, s10, v241
	s_nop 0
	v_addc_co_u32_e32 v83, vcc, 0, v81, vcc
	flat_load_dwordx4 v[92:95], v[80:81]
	flat_load_dwordx4 v[88:91], v[82:83]
	v_add_co_u32_e32 v82, vcc, s89, v80
	v_cvt_pk_bf16_f32 v100, v64, v65
	s_nop 0
	v_addc_co_u32_e32 v83, vcc, 0, v81, vcc
	v_add_co_u32_e32 v80, vcc, s90, v80
	v_cvt_pk_bf16_f32 v101, v66, v67
	s_nop 0
	v_addc_co_u32_e32 v81, vcc, 0, v81, vcc
	flat_load_dwordx4 v[84:87], v[82:83]
	s_nop 0
	flat_load_dwordx4 v[80:83], v[80:81]
	s_cmp_gt_u32 s65, 5
	s_cbranch_scc1 .Lmoba_drain_go
	v_cmp_eq_u32_e32 vcc, 0, v224
	s_and_b64 s[10:11], s[30:31], vcc
	s_and_saveexec_b64 s[8:9], s[10:11]
	s_cbranch_execz .Lmoba_dr_1
	s_mov_b64 s[10:11], src_shared_base
	s_cmp_lg_u32 s3, -1
	s_cselect_b32 s10, s3, 0
	s_cselect_b32 s11, s11, 0
	v_mov_b32_e32 v100, s10
	v_mov_b32_e32 v101, s11
	flat_store_dword v[100:101], v240 sc0 sc1
	s_waitcnt vmcnt(0)
.Lmoba_dr_1:
	s_or_b64 exec, exec, s[8:9]
	v_mov_b32_e32 v48, v112
	s_branch .Lmoba_drain_join
.Lmoba_drain_go:
	v_cvt_pk_bf16_f32 v102, v68, v69
	v_cvt_pk_bf16_f32 v103, v70, v71
	v_cvt_pk_bf16_f32 v104, v72, v73
	v_cvt_pk_bf16_f32 v105, v74, v75
	v_cvt_pk_bf16_f32 v106, v76, v77
	v_cvt_pk_bf16_f32 v107, v78, v79
	v_cvt_pk_bf16_f32 v108, v48, v49
	v_cvt_pk_bf16_f32 v109, v50, v51
	v_cvt_pk_bf16_f32 v110, v52, v53
	v_cvt_pk_bf16_f32 v111, v54, v55
	v_cvt_pk_bf16_f32 v114, v56, v57
	v_cvt_pk_bf16_f32 v115, v58, v59
	v_cvt_pk_bf16_f32 v116, v60, v61
	v_cvt_pk_bf16_f32 v117, v62, v63
	v_add3_u32 v97, v97, v225, s70
	ds_read_b64_tr_b16 v[118:119],v97 offset:0
	ds_read_b64_tr_b16 v[120:121],v97 offset:512
	ds_read_b64_tr_b16 v[122:123],v97 offset:1024
	ds_read_b64_tr_b16 v[124:125],v97 offset:1536
	ds_read_b64_tr_b16 v[126:127],v97 offset:2048
	ds_read_b64_tr_b16 v[128:129],v97 offset:2560
	ds_read_b64_tr_b16 v[130:131],v97 offset:3072
	ds_read_b64_tr_b16 v[132:133],v97 offset:3584
	s_waitcnt lgkmcnt(0)
	s_nop 0
	v_mfma_f32_32x32x16_bf16 v[16:31], v[100:103], v[118:121], v[16:31]
	ds_read_b64_tr_b16 v[118:119],v97 offset:4096
	ds_read_b64_tr_b16 v[120:121],v97 offset:4608
	v_mfma_f32_32x32x16_bf16 v[16:31], v[104:107], v[122:125], v[16:31]
	ds_read_b64_tr_b16 v[122:123],v97 offset:5120
	ds_read_b64_tr_b16 v[124:125],v97 offset:5632
	v_mfma_f32_32x32x16_bf16 v[16:31], v[108:111], v[126:129], v[16:31]
	ds_read_b64_tr_b16 v[126:127],v97 offset:6144
	ds_read_b64_tr_b16 v[128:129],v97 offset:6656
	v_mfma_f32_32x32x16_bf16 v[16:31], v[114:117], v[130:133], v[16:31]
	ds_read_b64_tr_b16 v[130:131],v97 offset:7168
	ds_read_b64_tr_b16 v[132:133],v97 offset:7680
	s_waitcnt lgkmcnt(0)
	v_mfma_f32_32x32x16_bf16 v[32:47], v[100:103], v[118:121], v[32:47]
	v_cmp_eq_u32_e32 vcc, 0, v224
	s_and_b64 s[10:11], s[30:31], vcc
	v_mfma_f32_32x32x16_bf16 v[32:47], v[104:107], v[122:125], v[32:47]
	v_mfma_f32_32x32x16_bf16 v[32:47], v[108:111], v[126:129], v[32:47]
	v_mfma_f32_32x32x16_bf16 v[32:47], v[114:117], v[130:133], v[32:47]
	s_and_saveexec_b64 s[8:9], s[10:11]
	s_cbranch_execz .LBB0_979
	s_mov_b64 s[10:11], src_shared_base
	s_cmp_lg_u32 s3, -1
	s_cselect_b32 s10, s3, 0
	s_cselect_b32 s11, s11, 0
	v_mov_b32_e32 v100, s10
	v_mov_b32_e32 v101, s11
	flat_store_dword v[100:101], v240 sc0 sc1
	s_waitcnt vmcnt(0)

; template<int THRL,int MODE,int DM,bool DRY=false> __device__ __forceinline__ void attn_unit(int b,int h,int qb,const bf16*Q,const bf16*__restrict__ K,const bf16*__restrict__ V,bf16*O,const bf16*__restrict__ Z,const float*__restrict__ XP,const int*__restrict__ TS,volatile unsigned*lw,unsigned nxt,cha ...
;     ...
;   if(lw!=nullptr&&tid==0)lw[0]=nxt;
;   {auto rr=__builtin_amdgcn_permlane32_swap(__float_as_uint(l_reg),__float_as_uint(l_reg),false,false);l_reg=__uint_as_float(rr[0])+__uint_as_float(rr[1]);}
;   if(hi==0)wsf[32+r32]=l_reg;asm volatile("s_waitcnt lgkmcnt(0)":::"memory");
.Lmoba_drain_join:
	v_mov_b32_e32 v49, v48
	s_nop 1
	v_permlane32_swap_b32_e32 v48, v49
	v_cmp_gt_u32_e32 vcc, 32, v239
	s_and_saveexec_b64 s[8:9], vcc
	s_cbranch_execz .LBB0_891
	v_add_f32_e32 v48, v48, v49
	ds_write_b32 v245, v48 offset:49280
	s_branch .LBB0_891
